# P7 K-loop restructured to 64 MFMA per barrier pair (2 segments per K-tile pair), split staging between wave groups, B1/At1 reads interleaved in MFMA stream
# speedup vs baseline: 1.0061x; 1.0061x over previous
.LBB0_757:
	s_and_b32 s22, s4, 3
	s_lshl_b32 s23, s3, 13
	s_lshl_b32 s24, s22, 9
	s_add_u32 s4, s56, 0x208800
	s_addc_u32 s5, s57, 0
	s_add_i32 m0, s36, 0x18000
	v_lshl_add_u64 v[8:9], s[4:5], 0, v[132:133]
	s_waitcnt vmcnt(0)
	s_barrier
	global_load_lds_dwordx4 v[8:9], off
	v_lshl_add_u64 v[8:9], s[4:5], 0, v[136:137]
	s_add_i32 m0, s36, 0x1a000
	s_mov_b64 s[14:15], 0x80
	s_add_i32 s77, s36, 0x8000
	s_add_i32 s78, s36, 0xa000
	global_load_lds_dwordx4 v[8:9], off
	v_lshl_add_u64 v[2:3], v[2:3], 0, s[14:15]
	s_mov_b32 m0, s77
	s_add_u32 s4, s56, 0x209000
	global_load_lds_dwordx4 v[2:3], off
	v_lshl_add_u64 v[2:3], v[4:5], 0, s[14:15]
	s_mov_b32 m0, s78
	s_addc_u32 s5, s57, 0
	global_load_lds_dwordx4 v[2:3], off
	s_add_i32 m0, s36, 0x1c000
	v_lshl_add_u64 v[2:3], s[4:5], 0, v[132:133]
	global_load_lds_dwordx4 v[2:3], off
	v_lshl_add_u64 v[2:3], s[4:5], 0, v[136:137]
	s_add_i32 m0, s36, 0x1e000
	v_and_b32_e32 v1, 15, v6
	global_load_lds_dwordx4 v[2:3], off
	v_bfe_u32 v2, v6, 4, 2
	v_lshlrev_b32_e32 v3, 4, v2
	v_lshl_or_b32 v3, v1, 6, v3
	v_lshlrev_b32_e32 v4, 2, v6
	v_lshlrev_b32_e32 v2, 11, v2
	v_lshlrev_b32_e32 v1, 4, v1
	v_and_b32_e32 v4, 32, v4
	v_or3_b32 v1, s24, v1, v2
	s_cmpk_lt_u32 s20, 0x100
	v_bfe_u32 v2, v6, 2, 4
	v_readlane_b32 s4, v249, 2
	v_bitop3_b32 v3, v3, s23, v4 bitop3:0xde
	s_waitcnt vmcnt(6)
	s_cselect_b64 s[30:31], -1, 0
	v_and_b32_e32 v4, 3, v6
	v_lshl_or_b32 v143, s3, 6, v2
	s_lshl_b32 s3, s4, 2
	v_and_b32_e32 v5, 60, v6
	v_lshlrev_b32_e32 v2, 3, v4
	s_and_b32 s82, s3, 28
	s_ashr_i32 s3, s4, 6
	v_lshl_or_b32 v142, v4, 6, v5
	v_lshl_or_b32 v144, s22, 5, v2
	s_ashr_i32 s79, s92, 31
	s_ashr_i32 s80, s4, 31
	s_bfe_u32 s81, s4, 0x30003
	s_add_i32 s82, s82, s3
	v_mov_b32_e32 v146, s2
	s_add_i32 s83, 0, 0x10000
	s_add_i32 s84, 0, 0x14000
	v_add_u32_e32 v145, 0, v3
	s_mov_b32 s85, 0x8080
	v_mov_b64_e32 v[138:139], 0xbff
	s_barrier
	v_readlane_b32 s5, v249, 3
	s_branch .LBB0_760

.LBB0_796:
	s_lshl_b32 s2, s90, 7
	s_add_u32 s20, s54, s2
	s_addc_u32 s21, s55, 0
	s_add_u32 s98, s20, 0x80
	s_addc_u32 s99, s21, 0
	s_add_u32 s4, s20, 0x100
	s_addc_u32 s5, s21, 0
	s_and_b64 s[2:3], s[60:61], exec
	s_cselect_b32 s5, s5, s43
	s_cselect_b32 s4, s4, s42
	s_mul_i32 s2, s90, 0x208800
	s_add_u32 s2, s56, s2
	s_addc_u32 s3, s57, 0
	s_add_u32 s100, s2, 0x208800
	s_addc_u32 s101, s3, 0
	s_add_u32 s22, s2, 0x411000
	s_addc_u32 s23, s3, 0
	s_and_b64 s[2:3], s[60:61], exec
	s_cselect_b32 s60, s22, s89
	s_cselect_b32 s61, s23, s35
	s_cmp_lt_u32 s18, 0x1000
	s_cbranch_scc0 .Lg2p7_0_hi
	s_add_u32 s2, s100, 0x0
	s_addc_u32 s3, s101, 0
	v_lshl_add_u64 v[140:141], s[2:3], 0, v[132:133]
	s_add_i32 m0, s18, 0x18000
	s_add_u32 s2, s2, 0x82200
	s_addc_u32 s3, s3, 0
	global_load_lds_dwordx4 v[140:141], off
	v_lshl_add_u64 v[212:213], s[2:3], 0, v[132:133]
	s_add_i32 m0, s18, 0x19000
	s_add_u32 s2, s2, 0x82200
	s_addc_u32 s3, s3, 0
	global_load_lds_dwordx4 v[212:213], off
	v_lshl_add_u64 v[140:141], s[2:3], 0, v[132:133]
	s_add_i32 m0, s18, 0x1a000
	s_add_u32 s2, s2, 0x82200
	s_addc_u32 s3, s3, 0
	global_load_lds_dwordx4 v[140:141], off
	v_lshl_add_u64 v[212:213], s[2:3], 0, v[132:133]
	s_add_i32 m0, s18, 0x1b000
	s_nop 0
	global_load_lds_dwordx4 v[212:213], off
	s_add_u32 s2, s98, 0x0
	s_addc_u32 s3, s99, 0
	v_lshl_add_u64 v[140:141], s[2:3], 0, v[130:131]
	s_add_i32 m0, s18, 0x8000
	s_add_u32 s2, s2, 0x41000
	s_addc_u32 s3, s3, 0
	global_load_lds_dwordx4 v[140:141], off
	v_lshl_add_u64 v[212:213], s[2:3], 0, v[130:131]
	s_add_i32 m0, s18, 0x9000
	s_add_u32 s2, s2, 0x41000
	s_addc_u32 s3, s3, 0
	global_load_lds_dwordx4 v[212:213], off
	v_lshl_add_u64 v[140:141], s[2:3], 0, v[130:131]
	s_add_i32 m0, s18, 0xa000
	s_add_u32 s2, s2, 0x41000
	s_addc_u32 s3, s3, 0
	global_load_lds_dwordx4 v[140:141], off
	v_lshl_add_u64 v[212:213], s[2:3], 0, v[130:131]
	s_add_i32 m0, s18, 0xb000
	s_nop 0
	global_load_lds_dwordx4 v[212:213], off
	s_branch .Lg2p7_0_done
.Lg2p7_0_hi:
	s_sub_u32 s2, s100, 0x81a00
	s_subb_u32 s3, s101, 0
	v_lshl_add_u64 v[140:141], s[2:3], 0, v[132:133]
	s_add_i32 m0, s18, 0x1b000
	s_add_u32 s2, s2, 0x82200
	s_addc_u32 s3, s3, 0
	global_load_lds_dwordx4 v[140:141], off
	v_lshl_add_u64 v[212:213], s[2:3], 0, v[132:133]
	s_add_i32 m0, s18, 0x1c000
	s_add_u32 s2, s2, 0x82200
	s_addc_u32 s3, s3, 0
	global_load_lds_dwordx4 v[212:213], off
	v_lshl_add_u64 v[140:141], s[2:3], 0, v[132:133]
	s_add_i32 m0, s18, 0x1d000
	s_add_u32 s2, s2, 0x82200
	s_addc_u32 s3, s3, 0
	global_load_lds_dwordx4 v[140:141], off
	v_lshl_add_u64 v[212:213], s[2:3], 0, v[132:133]
	s_add_i32 m0, s18, 0x1e000
	s_nop 0
	global_load_lds_dwordx4 v[212:213], off
	s_add_u32 s2, s98, 0xc3000
	s_addc_u32 s3, s99, 0
	v_lshl_add_u64 v[140:141], s[2:3], 0, v[130:131]
	s_add_i32 m0, s18, 0xb000
	s_add_u32 s2, s2, 0x41000
	s_addc_u32 s3, s3, 0
	global_load_lds_dwordx4 v[140:141], off
	v_lshl_add_u64 v[212:213], s[2:3], 0, v[130:131]
	s_add_i32 m0, s18, 0xc000
	s_add_u32 s2, s2, 0x41000
	s_addc_u32 s3, s3, 0
	global_load_lds_dwordx4 v[212:213], off
	v_lshl_add_u64 v[140:141], s[2:3], 0, v[130:131]
	s_add_i32 m0, s18, 0xd000
	s_add_u32 s2, s2, 0x41000
	s_addc_u32 s3, s3, 0
	global_load_lds_dwordx4 v[140:141], off
	v_lshl_add_u64 v[212:213], s[2:3], 0, v[130:131]
	s_add_i32 m0, s18, 0xe000
	s_nop 0
	global_load_lds_dwordx4 v[212:213], off
.Lg2p7_0_done:
	s_add_i32 s2, 0, 0x10000
	v_add_u32_e32 v147, s2, v1
	ds_read_b128 v[148:151], v147
	ds_read_b128 v[152:155], v147 offset:256
	ds_read_b128 v[156:159], v147 offset:8192
	ds_read_b128 v[160:163], v147 offset:8448
	ds_read_b128 v[180:183], v145
	ds_read_b128 v[184:187], v145 offset:1024
	ds_read_b128 v[188:191], v145 offset:2048
	ds_read_b128 v[192:195], v145 offset:3072
	ds_read_b128 v[196:199], v145 offset:4096
	ds_read_b128 v[200:203], v145 offset:5120
	ds_read_b128 v[204:207], v145 offset:6144
	ds_read_b128 v[208:211], v145 offset:7168
	s_waitcnt lgkmcnt(0)
	s_barrier
	s_setprio 1
	s_add_i32 s2, 0, 0x14000
	v_add_u32_e32 v147, s2, v1
	v_mfma_f32_16x16x32_bf16 v[126:129], v[148:151], v[180:183], v[126:129]
	v_mfma_f32_16x16x32_bf16 v[122:125], v[152:155], v[180:183], v[122:125]
	ds_read_b128 v[164:167], v147
	v_mfma_f32_16x16x32_bf16 v[110:113], v[148:151], v[188:191], v[110:113]
	v_mfma_f32_16x16x32_bf16 v[106:109], v[152:155], v[188:191], v[106:109]
	ds_read_b128 v[168:171], v147 offset:256
	v_mfma_f32_16x16x32_bf16 v[94:97], v[148:151], v[196:199], v[94:97]
	v_mfma_f32_16x16x32_bf16 v[90:93], v[152:155], v[196:199], v[90:93]
	ds_read_b128 v[172:175], v147 offset:8192
	v_mfma_f32_16x16x32_bf16 v[78:81], v[148:151], v[204:207], v[78:81]
	v_mfma_f32_16x16x32_bf16 v[74:77], v[152:155], v[204:207], v[74:77]
	ds_read_b128 v[176:179], v147 offset:8448
	v_mfma_f32_16x16x32_bf16 v[126:129], v[156:159], v[184:187], v[126:129]
	v_mfma_f32_16x16x32_bf16 v[122:125], v[160:163], v[184:187], v[122:125]
	ds_read_b128 v[216:219], v145 offset:16384
	v_mfma_f32_16x16x32_bf16 v[110:113], v[156:159], v[192:195], v[110:113]
	v_mfma_f32_16x16x32_bf16 v[106:109], v[160:163], v[192:195], v[106:109]
	ds_read_b128 v[220:223], v145 offset:17408
	v_mfma_f32_16x16x32_bf16 v[94:97], v[156:159], v[200:203], v[94:97]
	v_mfma_f32_16x16x32_bf16 v[90:93], v[160:163], v[200:203], v[90:93]
	ds_read_b128 v[224:227], v145 offset:18432
	v_mfma_f32_16x16x32_bf16 v[78:81], v[156:159], v[208:211], v[78:81]
	v_mfma_f32_16x16x32_bf16 v[74:77], v[160:163], v[208:211], v[74:77]
	ds_read_b128 v[228:231], v145 offset:19456
	s_waitcnt lgkmcnt(4)
	v_mfma_f32_16x16x32_bf16 v[118:121], v[164:167], v[180:183], v[118:121]
	v_mfma_f32_16x16x32_bf16 v[114:117], v[168:171], v[180:183], v[114:117]
	ds_read_b128 v[232:235], v145 offset:20480
	v_mfma_f32_16x16x32_bf16 v[102:105], v[164:167], v[188:191], v[102:105]
	v_mfma_f32_16x16x32_bf16 v[98:101], v[168:171], v[188:191], v[98:101]
	ds_read_b128 v[236:239], v145 offset:21504
	v_mfma_f32_16x16x32_bf16 v[86:89], v[164:167], v[196:199], v[86:89]
	v_mfma_f32_16x16x32_bf16 v[82:85], v[168:171], v[196:199], v[82:85]
	ds_read_b128 v[240:243], v145 offset:22528
	v_mfma_f32_16x16x32_bf16 v[70:73], v[164:167], v[204:207], v[70:73]
	v_mfma_f32_16x16x32_bf16 v[66:69], v[168:171], v[204:207], v[66:69]
	ds_read_b128 v[244:247], v145 offset:23552
	v_mfma_f32_16x16x32_bf16 v[118:121], v[172:175], v[184:187], v[118:121]
	v_mfma_f32_16x16x32_bf16 v[114:117], v[176:179], v[184:187], v[114:117]
	v_mfma_f32_16x16x32_bf16 v[102:105], v[172:175], v[192:195], v[102:105]
	v_mfma_f32_16x16x32_bf16 v[98:101], v[176:179], v[192:195], v[98:101]
	v_mfma_f32_16x16x32_bf16 v[86:89], v[172:175], v[200:203], v[86:89]
	v_mfma_f32_16x16x32_bf16 v[82:85], v[176:179], v[200:203], v[82:85]
	v_mfma_f32_16x16x32_bf16 v[70:73], v[172:175], v[208:211], v[70:73]
	v_mfma_f32_16x16x32_bf16 v[66:69], v[176:179], v[208:211], v[66:69]
	s_waitcnt lgkmcnt(0)
	v_mfma_f32_16x16x32_bf16 v[62:65], v[148:151], v[216:219], v[62:65]
	v_mfma_f32_16x16x32_bf16 v[58:61], v[152:155], v[216:219], v[58:61]
	v_mfma_f32_16x16x32_bf16 v[46:49], v[148:151], v[224:227], v[46:49]
	v_mfma_f32_16x16x32_bf16 v[42:45], v[152:155], v[224:227], v[42:45]
	v_mfma_f32_16x16x32_bf16 v[30:33], v[148:151], v[232:235], v[30:33]
	v_mfma_f32_16x16x32_bf16 v[26:29], v[152:155], v[232:235], v[26:29]
	v_mfma_f32_16x16x32_bf16 v[14:17], v[148:151], v[240:243], v[14:17]
	v_mfma_f32_16x16x32_bf16 v[10:13], v[152:155], v[240:243], v[10:13]
	v_mfma_f32_16x16x32_bf16 v[62:65], v[156:159], v[220:223], v[62:65]
	v_mfma_f32_16x16x32_bf16 v[58:61], v[160:163], v[220:223], v[58:61]
	v_mfma_f32_16x16x32_bf16 v[46:49], v[156:159], v[228:231], v[46:49]
	v_mfma_f32_16x16x32_bf16 v[42:45], v[160:163], v[228:231], v[42:45]
	v_mfma_f32_16x16x32_bf16 v[30:33], v[156:159], v[236:239], v[30:33]
	v_mfma_f32_16x16x32_bf16 v[26:29], v[160:163], v[236:239], v[26:29]
	v_mfma_f32_16x16x32_bf16 v[14:17], v[156:159], v[244:247], v[14:17]
	v_mfma_f32_16x16x32_bf16 v[10:13], v[160:163], v[244:247], v[10:13]
	v_mfma_f32_16x16x32_bf16 v[54:57], v[164:167], v[216:219], v[54:57]
	v_mfma_f32_16x16x32_bf16 v[50:53], v[168:171], v[216:219], v[50:53]
	v_mfma_f32_16x16x32_bf16 v[38:41], v[164:167], v[224:227], v[38:41]
	v_mfma_f32_16x16x32_bf16 v[34:37], v[168:171], v[224:227], v[34:37]
	v_mfma_f32_16x16x32_bf16 v[22:25], v[164:167], v[232:235], v[22:25]
	v_mfma_f32_16x16x32_bf16 v[18:21], v[168:171], v[232:235], v[18:21]
	v_mfma_f32_16x16x32_bf16 v[6:9], v[164:167], v[240:243], v[6:9]
	v_mfma_f32_16x16x32_bf16 v[2:5], v[168:171], v[240:243], v[2:5]
	v_mfma_f32_16x16x32_bf16 v[54:57], v[172:175], v[220:223], v[54:57]
	v_mfma_f32_16x16x32_bf16 v[50:53], v[176:179], v[220:223], v[50:53]
	v_mfma_f32_16x16x32_bf16 v[38:41], v[172:175], v[228:231], v[38:41]
	v_mfma_f32_16x16x32_bf16 v[34:37], v[176:179], v[228:231], v[34:37]
	v_mfma_f32_16x16x32_bf16 v[22:25], v[172:175], v[236:239], v[22:25]
	v_mfma_f32_16x16x32_bf16 v[18:21], v[176:179], v[236:239], v[18:21]
	v_mfma_f32_16x16x32_bf16 v[6:9], v[172:175], v[244:247], v[6:9]
	v_mfma_f32_16x16x32_bf16 v[2:5], v[176:179], v[244:247], v[2:5]
	s_setprio 0
	s_waitcnt vmcnt(0)
	s_barrier
	s_cmp_lt_u32 s18, 0x1000
	s_cbranch_scc0 .Lg2p7_1_hi
	s_add_u32 s2, s60, 0x0
	s_addc_u32 s3, s61, 0
	v_lshl_add_u64 v[140:141], s[2:3], 0, v[132:133]
	s_add_i32 m0, s18, 0x10000
	s_add_u32 s2, s2, 0x82200
	s_addc_u32 s3, s3, 0
	global_load_lds_dwordx4 v[140:141], off
	v_lshl_add_u64 v[212:213], s[2:3], 0, v[132:133]
	s_add_i32 m0, s18, 0x11000
	s_add_u32 s2, s2, 0x82200
	s_addc_u32 s3, s3, 0
	global_load_lds_dwordx4 v[212:213], off
	v_lshl_add_u64 v[140:141], s[2:3], 0, v[132:133]
	s_add_i32 m0, s18, 0x12000
	s_add_u32 s2, s2, 0x82200
	s_addc_u32 s3, s3, 0
	global_load_lds_dwordx4 v[140:141], off
	v_lshl_add_u64 v[212:213], s[2:3], 0, v[132:133]
	s_add_i32 m0, s18, 0x13000
	s_nop 0
	global_load_lds_dwordx4 v[212:213], off
	s_add_u32 s2, s4, 0x0
	s_addc_u32 s3, s5, 0
	v_lshl_add_u64 v[140:141], s[2:3], 0, v[130:131]
	s_add_i32 m0, s18, 0x0
	s_add_u32 s2, s2, 0x41000
	s_addc_u32 s3, s3, 0
	global_load_lds_dwordx4 v[140:141], off
	v_lshl_add_u64 v[212:213], s[2:3], 0, v[130:131]
	s_add_i32 m0, s18, 0x1000
	s_add_u32 s2, s2, 0x41000
	s_addc_u32 s3, s3, 0
	global_load_lds_dwordx4 v[212:213], off
	v_lshl_add_u64 v[140:141], s[2:3], 0, v[130:131]
	s_add_i32 m0, s18, 0x2000
	s_add_u32 s2, s2, 0x41000
	s_addc_u32 s3, s3, 0
	global_load_lds_dwordx4 v[140:141], off
	v_lshl_add_u64 v[212:213], s[2:3], 0, v[130:131]
	s_add_i32 m0, s18, 0x3000
	s_nop 0
	global_load_lds_dwordx4 v[212:213], off
	s_branch .Lg2p7_1_done
.Lg2p7_1_hi:
	s_sub_u32 s2, s60, 0x81a00
	s_subb_u32 s3, s61, 0
	v_lshl_add_u64 v[140:141], s[2:3], 0, v[132:133]
	s_add_i32 m0, s18, 0x13000
	s_add_u32 s2, s2, 0x82200
	s_addc_u32 s3, s3, 0
	global_load_lds_dwordx4 v[140:141], off
	v_lshl_add_u64 v[212:213], s[2:3], 0, v[132:133]
	s_add_i32 m0, s18, 0x14000
	s_add_u32 s2, s2, 0x82200
	s_addc_u32 s3, s3, 0
	global_load_lds_dwordx4 v[212:213], off
	v_lshl_add_u64 v[140:141], s[2:3], 0, v[132:133]
	s_add_i32 m0, s18, 0x15000
	s_add_u32 s2, s2, 0x82200
	s_addc_u32 s3, s3, 0
	global_load_lds_dwordx4 v[140:141], off
	v_lshl_add_u64 v[212:213], s[2:3], 0, v[132:133]
	s_add_i32 m0, s18, 0x16000
	s_nop 0
	global_load_lds_dwordx4 v[212:213], off
	s_add_u32 s2, s4, 0xc3000
	s_addc_u32 s3, s5, 0
	v_lshl_add_u64 v[140:141], s[2:3], 0, v[130:131]
	s_add_i32 m0, s18, 0x3000
	s_add_u32 s2, s2, 0x41000
	s_addc_u32 s3, s3, 0
	global_load_lds_dwordx4 v[140:141], off
	v_lshl_add_u64 v[212:213], s[2:3], 0, v[130:131]
	s_add_i32 m0, s18, 0x4000
	s_add_u32 s2, s2, 0x41000
	s_addc_u32 s3, s3, 0
	global_load_lds_dwordx4 v[212:213], off
	v_lshl_add_u64 v[140:141], s[2:3], 0, v[130:131]
	s_add_i32 m0, s18, 0x5000
	s_add_u32 s2, s2, 0x41000
	s_addc_u32 s3, s3, 0
	global_load_lds_dwordx4 v[140:141], off
	v_lshl_add_u64 v[212:213], s[2:3], 0, v[130:131]
	s_add_i32 m0, s18, 0x6000
	s_nop 0
	global_load_lds_dwordx4 v[212:213], off
.Lg2p7_1_done:
	s_add_i32 s2, 0, 0x18000
	v_add_u32_e32 v147, s2, v1
	ds_read_b128 v[148:151], v147
	ds_read_b128 v[152:155], v147 offset:256
	ds_read_b128 v[156:159], v147 offset:8192
	ds_read_b128 v[160:163], v147 offset:8448
	ds_read_b128 v[180:183], v145 offset:32768
	ds_read_b128 v[184:187], v145 offset:33792
	ds_read_b128 v[188:191], v145 offset:34816
	ds_read_b128 v[192:195], v145 offset:35840
	ds_read_b128 v[196:199], v145 offset:36864
	ds_read_b128 v[200:203], v145 offset:37888
	ds_read_b128 v[204:207], v145 offset:38912
	ds_read_b128 v[208:211], v145 offset:39936
	s_waitcnt lgkmcnt(0)
	s_barrier
	s_setprio 1
	s_add_i32 s2, 0, 0x1c000
	v_add_u32_e32 v147, s2, v1
	v_mfma_f32_16x16x32_bf16 v[126:129], v[148:151], v[180:183], v[126:129]
	v_mfma_f32_16x16x32_bf16 v[122:125], v[152:155], v[180:183], v[122:125]
	ds_read_b128 v[164:167], v147
	v_mfma_f32_16x16x32_bf16 v[110:113], v[148:151], v[188:191], v[110:113]
	v_mfma_f32_16x16x32_bf16 v[106:109], v[152:155], v[188:191], v[106:109]
	ds_read_b128 v[168:171], v147 offset:256
	v_mfma_f32_16x16x32_bf16 v[94:97], v[148:151], v[196:199], v[94:97]
	v_mfma_f32_16x16x32_bf16 v[90:93], v[152:155], v[196:199], v[90:93]
	ds_read_b128 v[172:175], v147 offset:8192
	v_mfma_f32_16x16x32_bf16 v[78:81], v[148:151], v[204:207], v[78:81]
	v_mfma_f32_16x16x32_bf16 v[74:77], v[152:155], v[204:207], v[74:77]
	ds_read_b128 v[176:179], v147 offset:8448
	v_mfma_f32_16x16x32_bf16 v[126:129], v[156:159], v[184:187], v[126:129]
	v_mfma_f32_16x16x32_bf16 v[122:125], v[160:163], v[184:187], v[122:125]
	ds_read_b128 v[216:219], v145 offset:49152
	v_mfma_f32_16x16x32_bf16 v[110:113], v[156:159], v[192:195], v[110:113]
	v_mfma_f32_16x16x32_bf16 v[106:109], v[160:163], v[192:195], v[106:109]
	ds_read_b128 v[220:223], v145 offset:50176
	v_mfma_f32_16x16x32_bf16 v[94:97], v[156:159], v[200:203], v[94:97]
	v_mfma_f32_16x16x32_bf16 v[90:93], v[160:163], v[200:203], v[90:93]
	ds_read_b128 v[224:227], v145 offset:51200
	v_mfma_f32_16x16x32_bf16 v[78:81], v[156:159], v[208:211], v[78:81]
	v_mfma_f32_16x16x32_bf16 v[74:77], v[160:163], v[208:211], v[74:77]
	ds_read_b128 v[228:231], v145 offset:52224
	s_waitcnt lgkmcnt(4)
	v_mfma_f32_16x16x32_bf16 v[118:121], v[164:167], v[180:183], v[118:121]
	v_mfma_f32_16x16x32_bf16 v[114:117], v[168:171], v[180:183], v[114:117]
	ds_read_b128 v[232:235], v145 offset:53248
	v_mfma_f32_16x16x32_bf16 v[102:105], v[164:167], v[188:191], v[102:105]
	v_mfma_f32_16x16x32_bf16 v[98:101], v[168:171], v[188:191], v[98:101]
	ds_read_b128 v[236:239], v145 offset:54272
	v_mfma_f32_16x16x32_bf16 v[86:89], v[164:167], v[196:199], v[86:89]
	v_mfma_f32_16x16x32_bf16 v[82:85], v[168:171], v[196:199], v[82:85]
	ds_read_b128 v[240:243], v145 offset:55296
	v_mfma_f32_16x16x32_bf16 v[70:73], v[164:167], v[204:207], v[70:73]
	v_mfma_f32_16x16x32_bf16 v[66:69], v[168:171], v[204:207], v[66:69]
	ds_read_b128 v[244:247], v145 offset:56320
	v_mfma_f32_16x16x32_bf16 v[118:121], v[172:175], v[184:187], v[118:121]
	v_mfma_f32_16x16x32_bf16 v[114:117], v[176:179], v[184:187], v[114:117]
	v_mfma_f32_16x16x32_bf16 v[102:105], v[172:175], v[192:195], v[102:105]
	v_mfma_f32_16x16x32_bf16 v[98:101], v[176:179], v[192:195], v[98:101]
	v_mfma_f32_16x16x32_bf16 v[86:89], v[172:175], v[200:203], v[86:89]
	v_mfma_f32_16x16x32_bf16 v[82:85], v[176:179], v[200:203], v[82:85]
	v_mfma_f32_16x16x32_bf16 v[70:73], v[172:175], v[208:211], v[70:73]
	v_mfma_f32_16x16x32_bf16 v[66:69], v[176:179], v[208:211], v[66:69]
	s_waitcnt lgkmcnt(0)
	v_mfma_f32_16x16x32_bf16 v[62:65], v[148:151], v[216:219], v[62:65]
	v_mfma_f32_16x16x32_bf16 v[58:61], v[152:155], v[216:219], v[58:61]
	v_mfma_f32_16x16x32_bf16 v[46:49], v[148:151], v[224:227], v[46:49]
	v_mfma_f32_16x16x32_bf16 v[42:45], v[152:155], v[224:227], v[42:45]
	v_mfma_f32_16x16x32_bf16 v[30:33], v[148:151], v[232:235], v[30:33]
	v_mfma_f32_16x16x32_bf16 v[26:29], v[152:155], v[232:235], v[26:29]
	v_mfma_f32_16x16x32_bf16 v[14:17], v[148:151], v[240:243], v[14:17]
	v_mfma_f32_16x16x32_bf16 v[10:13], v[152:155], v[240:243], v[10:13]
	v_mfma_f32_16x16x32_bf16 v[62:65], v[156:159], v[220:223], v[62:65]
	v_mfma_f32_16x16x32_bf16 v[58:61], v[160:163], v[220:223], v[58:61]
	v_mfma_f32_16x16x32_bf16 v[46:49], v[156:159], v[228:231], v[46:49]
	v_mfma_f32_16x16x32_bf16 v[42:45], v[160:163], v[228:231], v[42:45]
	v_mfma_f32_16x16x32_bf16 v[30:33], v[156:159], v[236:239], v[30:33]
	v_mfma_f32_16x16x32_bf16 v[26:29], v[160:163], v[236:239], v[26:29]
	v_mfma_f32_16x16x32_bf16 v[14:17], v[156:159], v[244:247], v[14:17]
	v_mfma_f32_16x16x32_bf16 v[10:13], v[160:163], v[244:247], v[10:13]
	v_mfma_f32_16x16x32_bf16 v[54:57], v[164:167], v[216:219], v[54:57]
	v_mfma_f32_16x16x32_bf16 v[50:53], v[168:171], v[216:219], v[50:53]
	v_mfma_f32_16x16x32_bf16 v[38:41], v[164:167], v[224:227], v[38:41]
	v_mfma_f32_16x16x32_bf16 v[34:37], v[168:171], v[224:227], v[34:37]
	v_mfma_f32_16x16x32_bf16 v[22:25], v[164:167], v[232:235], v[22:25]
	v_mfma_f32_16x16x32_bf16 v[18:21], v[168:171], v[232:235], v[18:21]
	v_mfma_f32_16x16x32_bf16 v[6:9], v[164:167], v[240:243], v[6:9]
	v_mfma_f32_16x16x32_bf16 v[2:5], v[168:171], v[240:243], v[2:5]
	v_mfma_f32_16x16x32_bf16 v[54:57], v[172:175], v[220:223], v[54:57]
	v_mfma_f32_16x16x32_bf16 v[50:53], v[176:179], v[220:223], v[50:53]
	v_mfma_f32_16x16x32_bf16 v[38:41], v[172:175], v[228:231], v[38:41]
	v_mfma_f32_16x16x32_bf16 v[34:37], v[176:179], v[228:231], v[34:37]
	v_mfma_f32_16x16x32_bf16 v[22:25], v[172:175], v[236:239], v[22:25]
	v_mfma_f32_16x16x32_bf16 v[18:21], v[176:179], v[236:239], v[18:21]
	v_mfma_f32_16x16x32_bf16 v[6:9], v[172:175], v[244:247], v[6:9]
	v_mfma_f32_16x16x32_bf16 v[2:5], v[176:179], v[244:247], v[2:5]
	s_setprio 0
	s_waitcnt vmcnt(0)
	s_barrier
	s_add_i32 s2, s90, 2
	s_cmp_gt_u32 s90, 61
	s_cbranch_scc1 .LBB0_802
	s_mov_b32 s90, s2
	s_branch .LBB0_767

	.amdhsa_kernel _Z6mk_fwd4Args
		.amdhsa_group_segment_fixed_size 0
		.amdhsa_private_segment_fixed_size 0
		.amdhsa_kernarg_size 456
		.amdhsa_user_sgpr_count 2
		.amdhsa_user_sgpr_dispatch_ptr 0
		.amdhsa_user_sgpr_queue_ptr 0
		.amdhsa_user_sgpr_kernarg_segment_ptr 1
		.amdhsa_user_sgpr_dispatch_id 0
		.amdhsa_user_sgpr_kernarg_preload_length 0
		.amdhsa_user_sgpr_kernarg_preload_offset 0
		.amdhsa_user_sgpr_private_segment_size 0
		.amdhsa_uses_dynamic_stack 0
		.amdhsa_enable_private_segment 0
		.amdhsa_system_sgpr_workgroup_id_x 1
		.amdhsa_system_sgpr_workgroup_id_y 0
		.amdhsa_system_sgpr_workgroup_id_z 0
		.amdhsa_system_sgpr_workgroup_info 0
		.amdhsa_system_vgpr_workitem_id 0
		.amdhsa_next_free_vgpr 250
		.amdhsa_next_free_sgpr 102
		.amdhsa_accum_offset 252
		.amdhsa_reserve_vcc 1
		.amdhsa_float_round_mode_32 0
		.amdhsa_float_round_mode_16_64 0
		.amdhsa_float_denorm_mode_32 3
		.amdhsa_float_denorm_mode_16_64 3
		.amdhsa_dx10_clamp 1
		.amdhsa_ieee_mode 1
		.amdhsa_fp16_overflow 0
		.amdhsa_tg_split 0
		.amdhsa_exception_fp_ieee_invalid_op 0
		.amdhsa_exception_fp_denorm_src 0
		.amdhsa_exception_fp_ieee_div_zero 0
		.amdhsa_exception_fp_ieee_overflow 0
		.amdhsa_exception_fp_ieee_underflow 0
		.amdhsa_exception_fp_ieee_inexact 0
		.amdhsa_exception_int_div_zero 0
	.end_amdhsa_kernel

amdhsa.kernels:
  - .agpr_count:     0
    .args:
      - .offset:         0
        .size:           200
        .value_kind:     by_value
      - .offset:         200
        .size:           4
        .value_kind:     hidden_block_count_x
      - .offset:         204
        .size:           4
        .value_kind:     hidden_block_count_y
      - .offset:         208
        .size:           4
        .value_kind:     hidden_block_count_z
      - .offset:         212
        .size:           2
        .value_kind:     hidden_group_size_x
      - .offset:         214
        .size:           2
        .value_kind:     hidden_group_size_y
      - .offset:         216
        .size:           2
        .value_kind:     hidden_group_size_z
      - .offset:         218
        .size:           2
        .value_kind:     hidden_remainder_x
      - .offset:         220
        .size:           2
        .value_kind:     hidden_remainder_y
      - .offset:         222
        .size:           2
        .value_kind:     hidden_remainder_z
      - .offset:         240
        .size:           8
        .value_kind:     hidden_global_offset_x
      - .offset:         248
        .size:           8
        .value_kind:     hidden_global_offset_y
      - .offset:         256
        .size:           8
        .value_kind:     hidden_global_offset_z
      - .offset:         264
        .size:           2
        .value_kind:     hidden_grid_dims
      - .offset:         320
        .size:           4
        .value_kind:     hidden_dynamic_lds_size
    .group_segment_fixed_size: 0
    .kernarg_segment_align: 8
    .kernarg_segment_size: 456
    .language:       OpenCL C
    .language_version:
      - 2
      - 0
    .max_flat_workgroup_size: 512
    .name:           _Z6mk_fwd4Args
    .private_segment_fixed_size: 0
    .sgpr_count:     108
    .sgpr_spill_count: 79
    .symbol:         _Z6mk_fwd4Args.kd
    .uniform_work_group_size: 1
    .uses_dynamic_stack: false
    .vgpr_count:     250
    .vgpr_spill_count: 0
    .wavefront_size: 64
